# DSA epilogue: gate rows prefetched by LDS-DMA at item start, fp8 outputs transposed through LDS into coalesced dwordx4 stores; barrier at memory-item entry
# baseline (speedup 1.0000x reference)
; template <int DQK, int W1, int DV, int VW, int MODE> ...
;     ...
;   int tid0 = threadIdx.x; asm volatile("" : "+v"(tid0));
;   const int lane = tid0 & 63, r32 = lane & 31, hi = lane >> 5;
;   const int wv = __builtin_amdgcn_readfirstlane(tid0 >> 6);
;   const unsigned lds0 = (unsigned)(uintptr_t)smem;
;   bf16x8 qf[ND];
; #pragma unroll
;   for (int d0 = 0; d0 < ND; ++d0) qf[d0] = *(const bf16x8*)(qrow + d0 * 16 + hi * 8);
;   f32x16 o[NCB];
; #pragma unroll
;   for (int cb = 0; cb < NCB; ++cb)
; #pragma unroll
;     for (int r = 0; r < 16; ++r) o[cb][r] = 0.f;
;   f32x16 negm = {0.f, 0.f, 0.f, 0.f, 0.f, 0.f, 0.f, 0.f, 0.f, 0.f, 0.f, 0.f, 0.f, 0.f, 0.f, 0.f};
;   float m = m_init, l = (hi == 0) ? l_init : 0.f;
;   const unsigned klane = (unsigned)(r32 * KSTR + hi * 16);
;   const unsigned vlane = (unsigned)(64 * KSTR + vcb0 * 4096 + ((lane >> 4) & 1) * 32 + (lane & 3) * 8 + (4 * hi + ((lane & 15) >> 2)) * 64);
;   unsigned mwn[2] = {0u, 0u};
;   constexpr int NKS = (NKI + 7) / 8, NVS = (NVI + 7) / 8;
;   const u16* kptr[NKS]; int kstr[NKS]; const u16* vptr[NVS];
;   if (MODE != 2) {
;     int ln = threadIdx.x & 63; asm volatile("" : "+v"(ln));
; #pragma unroll
;     for (int ii = 0; ii < NKS; ++ii) {
;       const int i = wv + 8 * ii, ob = i * 1024 + ln * 16, row = ob / KSTR;
;       int c = (ob - row * KSTR) >> 4; c = (c >= KCH) ? 0 : c;
;       const bool seg1 = c < W1 / 8;
;       kptr[ii] = seg1 ? (k1 + ((kbase0 + row) * ldk1 + c * 8)) : (k2 + ((kbase0 + row) * ldk2 + (c - W1 / 8) * 8));
;       kstr[ii] = seg1 ? 64 * ldk1 : 64 * ldk2;
; __global__ void __launch_bounds__(512, 2) mega(Params p) {
;     ...
;           const int it = item - nself, b = it / 64, mh = (it % 64) / 16, qb = it % 16;
;           const size_t brow = (size_t)b * SEQ;
;           const int tq0 = qb * 128 + 32 * (wv >> 1), tq = tq0 + r32, vh = wv & 1;
;           attn_core<256, 256, 128, 256, 3>(memkv + (size_t)b * 256 * 8192 + mh * 256, 8192, nullptr, 0, memkv + (size_t)b * 256 * 8192 + 1024 + mh * 256, 8192,
;                                           256, 0, 4, mgb + (brow + tq) * ldmg + mqcol + mh * 256, tq, tq0, 0.0625f * LOG2E, 4 * vh,
;                                           (u16*)(Y8 + (brow + tq) * 3072 + 2048 + mh * 256 + 128 * vh), mgb + (brow + tq) * ldmg + gatecol + 2048 + mh * 256 + 128 * vh,
;                                           nullptr, nullptr, 0.f, -1e29f, 0.f, smem);
.LBB0_1248:
	s_barrier
	s_sub_i32 s0, s26, s22
	s_lshl_b32 s8, s26, 7
	s_lshr_b32 s54, s0, 6
	s_and_b32 s8, s8, 0x780
	s_lshl_b64 s[0:1], s[54:55], 11
	v_add_u32_e32 v0, s8, v246
	s_lshl_b64 s[8:9], s[54:55], 22
	v_lshl_add_u64 v[166:167], s[0:1], 0, v[0:1]
	s_add_u32 s10, s59, s8
	v_mad_u64_u32 v[2:3], s[0:1], v166, s24, 0
	s_addc_u32 s11, s65, s9
	s_lshl_b32 s8, s26, 4
	v_mad_u32_u24 v3, v167, s24, v3
	s_and_b32 s54, s8, 0x300
	v_lshl_add_u64 v[164:165], v[2:3], 1, s[6:7]
	s_mov_b32 s73, s55
	s_lshl_b32 s8, s54, 1
	s_mov_b32 s9, s55
	v_lshl_add_u64 v[2:3], v[164:165], 0, s[72:73]
	v_lshl_add_u64 v[4:5], v[2:3], 0, s[8:9]
	v_mov_b32_e32 v2, v179
	s_add_u32 s94, s10, s8
	v_bfe_u32 v3, v2, 5, 1
	v_lshlrev_b32_e32 v0, 4, v3
	v_lshl_add_u64 v[4:5], v[4:5], 0, v[0:1]
	global_load_dwordx4 v[158:161], v[4:5], off
	global_load_dwordx4 v[154:157], v[4:5], off offset:32
	global_load_dwordx4 v[150:153], v[4:5], off offset:64
	global_load_dwordx4 v[146:149], v[4:5], off offset:96
	global_load_dwordx4 v[142:145], v[4:5], off offset:128
	global_load_dwordx4 v[138:141], v[4:5], off offset:160
	global_load_dwordx4 v[134:137], v[4:5], off offset:192
	global_load_dwordx4 v[130:133], v[4:5], off offset:224
	global_load_dwordx4 v[126:129], v[4:5], off offset:256
	global_load_dwordx4 v[122:125], v[4:5], off offset:288
	global_load_dwordx4 v[118:121], v[4:5], off offset:320
	global_load_dwordx4 v[114:117], v[4:5], off offset:352
	global_load_dwordx4 v[110:113], v[4:5], off offset:384
	global_load_dwordx4 v[106:109], v[4:5], off offset:416
	global_load_dwordx4 v[102:105], v[4:5], off offset:448
	global_load_dwordx4 v[98:101], v[4:5], off offset:480
	v_readfirstlane_b32 s0, v2
	s_addc_u32 s95, s11, 0
	s_ashr_i32 s27, s0, 6
	v_mov_b32_e32 v4, v244
	s_lshl_b32 s28, s27, 10
	s_mov_b32 s0, 0x3e0f83e1
	v_lshl_add_u32 v0, v4, 4, s28
	v_mul_hi_i32 v5, v0, s0
	v_lshrrev_b32_e32 v6, 31, v5
	v_ashrrev_i32_e32 v5, 7, v5
	v_add_u32_e32 v5, v5, v6
	s_movk_i32 s0, 0xfdf0
	v_mad_i32_i24 v6, v5, s0, v0
	s_movk_i32 s0, 0x1f1
	v_ashrrev_i32_e32 v7, 1, v6
	v_cmp_gt_i32_e32 vcc, s0, v6
	s_cmp_lt_i32 s27, 33
	s_cselect_b64 s[0:1], -1, 0
	v_cndmask_b32_e32 v6, 0, v7, vcc
	v_lshl_add_u32 v6, v5, 13, v6
	v_ashrrev_i32_e32 v7, 31, v6
	s_cmp_gt_i32 s27, 32
	v_lshl_add_u64 v[168:169], v[6:7], 1, s[94:95]
	s_cbranch_scc1 .LBB0_1250
	s_add_i32 m0, s28, 0
	s_nop 0
	global_load_lds_dwordx4 v[168:169], off
	v_lshl_add_u64 v[168:169], v[168:169], 0, s[60:61]

; template <int DQK, int W1, int DV, int VW, int MODE> ...
;     ...
;   stage_tile(kbase0, 0);
;   asm volatile("s_waitcnt vmcnt(0)" ::: "memory");
;   __syncthreads();
;     ...
;   u32x2 ggv[NCB * 4];
; #pragma unroll
;   for (int cb = 0; cb < NCB; ++cb)
; #pragma unroll
;     for (int g = 0; g < 4; ++g) ggv[cb * 4 + g] = *(const u32x2*)(grow + 32 * cb + 8 * g + 4 * hi);
.Ldsa_p1_done:
	v_lshlrev_b32_e32 v210, 2, v82
	s_lshl_b32 s100, s29, 5
	v_add_u32_e32 v210, s100, v210
	v_mov_b32_e32 v211, v1
	v_lshl_add_u64 v[210:211], v[96:97], 0, v[210:211]
	s_add_i32 m0, s18, 0xd000
	v_and_b32_e32 v208, 31, v179
	global_load_lds_dwordx4 v[210:211], off
	v_lshlrev_b32_e32 v208, 4, v208
	v_add_u32_e32 v208, 0xd000, v208
	v_lshlrev_b32_e32 v212, 2, v82
	v_mov_b32_e32 v213, v1
	v_lshl_add_u64 v[212:213], v[84:85], 0, v[212:213]
	s_mov_b64 s[100:101], 0x24a0
	v_lshl_add_u64 v[212:213], v[212:213], 0, s[100:101]
	s_lshl_b32 s100, s29, 12
	s_add_i32 s100, s100, 0xf000
	s_mov_b32 m0, s100
	s_nop 0
	global_load_lds_dwordx4 v[212:213], off
	s_add_i32 m0, s100, 992
	s_nop 0
	global_load_lds_dwordx4 v[212:213], off offset:32
	s_add_i32 m0, s100, 1984
	s_nop 0
	global_load_lds_dwordx4 v[212:213], off offset:64
	s_add_i32 m0, s100, 2976
	s_nop 0
	global_load_lds_dwordx4 v[212:213], off offset:96
	s_waitcnt vmcnt(0)
	v_or3_b32 v99, v0, v2, s0
	v_mov_b32_e32 v0, v1
	v_mov_b32_e32 v2, v1
	v_mov_b32_e32 v3, v1
	v_mov_b32_e32 v4, v1
	v_mov_b32_e32 v5, v1
	v_mov_b32_e32 v6, v1
	v_mov_b32_e32 v7, v1
	v_mov_b32_e32 v8, v1
	v_mov_b32_e32 v9, v1
	v_mov_b32_e32 v10, v1
	v_mov_b32_e32 v11, v1
	v_mov_b32_e32 v12, v1
	v_mov_b32_e32 v13, v1
	v_mov_b64_e32 v[32:33], v[14:15]
	v_mov_b64_e32 v[30:31], v[12:13]
	v_mov_b64_e32 v[28:29], v[10:11]
	v_mov_b64_e32 v[26:27], v[8:9]
	v_mov_b64_e32 v[24:25], v[6:7]
	v_mov_b64_e32 v[22:23], v[4:5]
	v_mov_b64_e32 v[20:21], v[2:3]
	v_mov_b64_e32 v[18:19], v[0:1]
	v_mov_b64_e32 v[16:17], v[14:15]
	s_add_i32 s73, s18, 0
	s_add_i32 s86, s28, 0x7a1
	s_waitcnt lgkmcnt(0)
	v_mov_b32_e32 v89, v88
	s_add_i32 s87, s69, 1
	v_sub_u32_e32 v118, v247, v82
	s_mov_b32 s0, 0
	v_mov_b32_e32 v119, 0
	v_mov_b32_e32 v98, 0xefa18f08
	s_mov_b32 s94, 64
	v_mov_b64_e32 v[14:15], v[12:13]
	v_mov_b64_e32 v[12:13], v[10:11]
	v_mov_b64_e32 v[10:11], v[8:9]
	v_mov_b64_e32 v[8:9], v[6:7]
	v_mov_b64_e32 v[6:7], v[4:5]
	v_mov_b64_e32 v[4:5], v[2:3]
	v_mov_b64_e32 v[2:3], v[0:1]
	s_mov_b64 s[28:29], 0xf4000
	s_mov_b32 s100, 0
	s_mov_b32 s101, 0x8800
	s_waitcnt vmcnt(0)
	s_barrier
	s_add_i32 s95, s0, 1
	s_cmp_ge_u32 s0, s69
	s_cbranch_scc1 .LBB0_1333

; DI float bf2f(unsigned b) { return __uint_as_float(b << 16); }
; template <int DQK, int W1, int DV, int VW, int MODE> ...
;     ...
;   const float inv = __builtin_amdgcn_rcpf(xhalf_sum(l));
;   u32x2 ggv[NCB * 4];
; #pragma unroll
;   for (int cb = 0; cb < NCB; ++cb)
; #pragma unroll
;     for (int g = 0; g < 4; ++g) ggv[cb * 4 + g] = *(const u32x2*)(grow + 32 * cb + 8 * g + 4 * hi);
;   __builtin_amdgcn_sched_barrier(0);
; #pragma unroll
;   for (int cb = 0; cb < NCB; ++cb)
; #pragma unroll
;     for (int g = 0; g < 4; ++g) {
;       const int dv = 32 * cb + 8 * g + 4 * hi;
;       const u32x2 gg = ggv[cb * 4 + g];
;       float gv[4] = {bf2f(gg[0] & 0xffffu), bf2f(gg[0] >> 16), bf2f(gg[1] & 0xffffu), bf2f(gg[1] >> 16)};
;       float ov[4];
; #pragma unroll
;       for (int j = 0; j < 4; ++j) {
;         const float sg = gv[j] * __builtin_amdgcn_rcpf(1.f + __builtin_amdgcn_exp2f(-LOG2E * gv[j]));
;         ov[j] = o[cb][4 * g + j] * inv * sg;
;       }
;       *(unsigned*)((unsigned char*)yrow + dv) = pk4_fp8(ov[0] * Y_SCALE, ov[1] * Y_SCALE, ov[2] * Y_SCALE, ov[3] * Y_SCALE);
;       __builtin_amdgcn_sched_barrier(0);
;     }
.LBB0_1348:
	v_mov_b64_e32 v[34:35], s[82:83]
	v_mov_b32_e32 v0, v119
	v_mad_u64_u32 v[34:35], s[0:1], v86, s34, v[34:35]
	s_nop 0
	v_permlane32_swap_b32_e32 v119, v0
	v_mad_i32_i24 v35, v87, s34, v35
	v_add_f32_e32 v54, v119, v0
	v_lshl_add_u64 v[46:47], v[34:35], 0, s[10:11]
	v_mov_b32_e32 v83, v1
	v_and_b32_e32 v48, 31, v179
	s_lshl_b32 s0, s73, 2
	v_lshlrev_b32_e32 v48, 4, v48
	s_add_i32 s0, s0, 0xf000
	v_lshl_add_u32 v48, v82, 1, v48
	v_add_u32_e32 v48, s0, v48
	v_and_b32_e32 v212, 31, v179
	s_lshl_b32 s0, s73, 1
	v_mul_u32_u24_e32 v212, 0x48, v212
	s_lshr_b32 s1, s73, 2
	v_add_u32_e32 v212, v82, v212
	s_add_i32 s0, s0, s1
	v_and_b32_e32 v213, 63, v179
	s_add_i32 s0, s0, 0x17000
	v_add_u32_e32 v212, s0, v212
	v_lshrrev_b32_e32 v210, 2, v213
	v_and_b32_e32 v213, 3, v213
	v_mul_u32_u24_e32 v211, 0x48, v210
	v_lshlrev_b32_e32 v213, 4, v213
	v_mul_u32_u24_e32 v210, 0xc00, v210
	v_add3_u32 v211, v211, v213, s0
	v_add_u32_e32 v210, v210, v213
	ds_read_b64 v[50:51], v48
	ds_read_b64 v[52:53], v48 offset:512
	ds_read_b64 v[44:45], v48 offset:1024
	ds_read_b64 v[42:43], v48 offset:1536
	ds_read_b64 v[40:41], v48 offset:2048
	ds_read_b64 v[38:39], v48 offset:2560
	ds_read_b64 v[36:37], v48 offset:3072
	ds_read_b64 v[34:35], v48 offset:3584
	v_rcp_f32_e32 v0, v54
	s_waitcnt lgkmcnt(0)
	v_lshlrev_b32_e32 v48, 16, v50
	v_mul_f32_e32 v54, 0xbfb8aa3b, v48
	v_exp_f32_e32 v54, v54
	v_and_b32_e32 v49, 0xffff0000, v50
	v_mul_f32_e32 v18, v18, v0
	v_lshlrev_b32_e32 v50, 16, v51
	v_add_f32_e32 v54, 1.0, v54
	v_rcp_f32_e32 v54, v54
	v_mul_f32_e32 v19, v19, v0
	v_and_b32_e32 v51, 0xffff0000, v51
	v_mul_f32_e32 v20, v20, v0
	v_mul_f32_e32 v48, v54, v48
	v_mul_f32_e32 v18, v18, v48
	v_mul_f32_e32 v48, 0xbfb8aa3b, v49
	v_exp_f32_e32 v48, v48
	v_mul_f32_e32 v21, v21, v0
	v_mul_f32_e32 v18, 0x41800000, v18
	v_med3_f32 v18, v18, s93, v223
	v_add_f32_e32 v48, 1.0, v48
	v_rcp_f32_e32 v48, v48
	s_nop 0
	v_mul_f32_e32 v48, v48, v49
	v_mul_f32_e32 v19, v19, v48
	v_mul_f32_e32 v48, 0xbfb8aa3b, v50
	v_exp_f32_e32 v48, v48
	v_mul_f32_e32 v19, 0x41800000, v19
	v_med3_f32 v19, v19, s93, v223
	v_add_f32_e32 v48, 1.0, v48
	v_rcp_f32_e32 v48, v48
	s_nop 0
	v_mul_f32_e32 v48, v48, v50
	v_mul_f32_e32 v20, v20, v48
	v_mul_f32_e32 v48, 0xbfb8aa3b, v51
	v_exp_f32_e32 v48, v48
	v_mul_f32_e32 v20, 0x41800000, v20
	v_add_f32_e32 v48, 1.0, v48
	v_rcp_f32_e32 v48, v48
	s_nop 0
	v_mul_f32_e32 v48, v48, v51
	v_mul_f32_e32 v21, v21, v48
	v_mov_b32_e32 v48, v1
	v_cvt_pk_fp8_f32 v48, v18, v19
	v_mul_f32_e32 v21, 0x41800000, v21
	v_med3_f32 v18, v20, s93, v223
	v_med3_f32 v19, v21, s93, v223
	v_cvt_pk_fp8_f32 v48, v18, v19 op_sel:[0,0,1]
	v_lshl_add_u64 v[18:19], v[46:47], 0, v[82:83]
	ds_write_b32 v212, v48
	s_waitcnt vmcnt(7)
	v_lshlrev_b32_e32 v20, 16, v52
	v_mul_f32_e32 v48, 0xbfb8aa3b, v20
	v_exp_f32_e32 v48, v48
	v_and_b32_e32 v21, 0xffff0000, v52
	v_mul_f32_e32 v22, v22, v0
	v_lshlrev_b32_e32 v46, 16, v53
	v_add_f32_e32 v48, 1.0, v48
	v_rcp_f32_e32 v48, v48
	v_and_b32_e32 v47, 0xffff0000, v53
	v_mul_f32_e32 v20, v48, v20
	v_mul_f32_e32 v20, v22, v20
	v_mul_f32_e32 v22, 0xbfb8aa3b, v21
	v_exp_f32_e32 v22, v22
	v_mul_f32_e32 v20, 0x41800000, v20
	v_med3_f32 v20, v20, s93, v223
	v_add_f32_e32 v22, 1.0, v22
	v_rcp_f32_e32 v22, v22
	s_nop 0
	v_mul_f32_e32 v21, v22, v21
	v_mul_f32_e32 v22, v23, v0
	v_mul_f32_e32 v21, v22, v21
	v_mul_f32_e32 v22, 0xbfb8aa3b, v46
	v_exp_f32_e32 v22, v22
	v_mul_f32_e32 v23, v24, v0
	v_mul_f32_e32 v24, v25, v0
	v_mul_f32_e32 v21, 0x41800000, v21
	v_add_f32_e32 v22, 1.0, v22
	v_rcp_f32_e32 v22, v22
	v_med3_f32 v21, v21, s93, v223
	v_mul_f32_e32 v22, v22, v46
	v_mul_f32_e32 v22, v23, v22
	v_mul_f32_e32 v23, 0xbfb8aa3b, v47
	v_exp_f32_e32 v23, v23
	v_mul_f32_e32 v22, 0x41800000, v22
	v_add_f32_e32 v23, 1.0, v23
	v_rcp_f32_e32 v23, v23
	s_nop 0
	v_mul_f32_e32 v23, v23, v47
	v_mul_f32_e32 v23, v24, v23
	v_mov_b32_e32 v24, v1
	v_cvt_pk_fp8_f32 v24, v20, v21
	v_mul_f32_e32 v23, 0x41800000, v23
	v_med3_f32 v20, v22, s93, v223
	v_med3_f32 v21, v23, s93, v223
	v_cvt_pk_fp8_f32 v24, v20, v21 op_sel:[0,0,1]
	ds_write_b32 v212, v24 offset:8
	s_waitcnt vmcnt(7)
	v_lshlrev_b32_e32 v20, 16, v44
	v_mul_f32_e32 v24, 0xbfb8aa3b, v20
	v_exp_f32_e32 v24, v24
	v_and_b32_e32 v21, 0xffff0000, v44
	v_lshlrev_b32_e32 v22, 16, v45
	v_and_b32_e32 v23, 0xffff0000, v45
	v_add_f32_e32 v24, 1.0, v24
	v_rcp_f32_e32 v24, v24
	s_nop 0
	v_mul_f32_e32 v20, v24, v20
	v_mul_f32_e32 v24, v26, v0
	v_mul_f32_e32 v20, v24, v20
	v_mul_f32_e32 v24, 0xbfb8aa3b, v21
	v_exp_f32_e32 v24, v24
	v_mul_f32_e32 v20, 0x41800000, v20
	v_med3_f32 v20, v20, s93, v223
	v_add_f32_e32 v24, 1.0, v24
	v_rcp_f32_e32 v24, v24
	s_nop 0
	v_mul_f32_e32 v21, v24, v21
	v_mul_f32_e32 v24, v27, v0
	v_mul_f32_e32 v21, v24, v21
	v_mul_f32_e32 v24, 0xbfb8aa3b, v22
	v_exp_f32_e32 v24, v24
	v_mul_f32_e32 v21, 0x41800000, v21
	v_med3_f32 v21, v21, s93, v223
	v_add_f32_e32 v24, 1.0, v24
	v_rcp_f32_e32 v24, v24
	s_nop 0
	v_mul_f32_e32 v22, v24, v22
	v_mul_f32_e32 v24, v28, v0
	v_mul_f32_e32 v22, v24, v22
	v_mul_f32_e32 v24, 0xbfb8aa3b, v23
	v_exp_f32_e32 v24, v24
	v_mul_f32_e32 v22, 0x41800000, v22
	v_add_f32_e32 v24, 1.0, v24
	v_rcp_f32_e32 v24, v24
	s_nop 0
	v_mul_f32_e32 v23, v24, v23
	v_mul_f32_e32 v24, v29, v0
	v_mul_f32_e32 v23, v24, v23
	v_mov_b32_e32 v24, v1
	v_cvt_pk_fp8_f32 v24, v20, v21
	v_mul_f32_e32 v23, 0x41800000, v23
	v_med3_f32 v20, v22, s93, v223
	v_med3_f32 v21, v23, s93, v223
	v_cvt_pk_fp8_f32 v24, v20, v21 op_sel:[0,0,1]
	ds_write_b32 v212, v24 offset:16
	s_waitcnt vmcnt(7)
; DI float bf2f(unsigned b) { return __uint_as_float(b << 16); }
; template <int DQK, int W1, int DV, int VW, int MODE> ...
;     ...
; #pragma unroll
;   for (int cb = 0; cb < NCB; ++cb)
; #pragma unroll
;     for (int g = 0; g < 4; ++g) {
;       const int dv = 32 * cb + 8 * g + 4 * hi;
;       const u32x2 gg = ggv[cb * 4 + g];
;       float gv[4] = {bf2f(gg[0] & 0xffffu), bf2f(gg[0] >> 16), bf2f(gg[1] & 0xffffu), bf2f(gg[1] >> 16)};
;       float ov[4];
; #pragma unroll
;       for (int j = 0; j < 4; ++j) {
;         const float sg = gv[j] * __builtin_amdgcn_rcpf(1.f + __builtin_amdgcn_exp2f(-LOG2E * gv[j]));
;         ov[j] = o[cb][4 * g + j] * inv * sg;
;       }
;       *(unsigned*)((unsigned char*)yrow + dv) = pk4_fp8(ov[0] * Y_SCALE, ov[1] * Y_SCALE, ov[2] * Y_SCALE, ov[3] * Y_SCALE);
;       __builtin_amdgcn_sched_barrier(0);
;     }
	v_lshlrev_b32_e32 v20, 16, v42
	v_mul_f32_e32 v24, 0xbfb8aa3b, v20
	v_exp_f32_e32 v24, v24
	v_and_b32_e32 v21, 0xffff0000, v42
	v_lshlrev_b32_e32 v22, 16, v43
	v_and_b32_e32 v23, 0xffff0000, v43
	v_add_f32_e32 v24, 1.0, v24
	v_rcp_f32_e32 v24, v24
	s_nop 0
	v_mul_f32_e32 v20, v24, v20
	v_mul_f32_e32 v24, v30, v0
	v_mul_f32_e32 v20, v24, v20
	v_mul_f32_e32 v24, 0xbfb8aa3b, v21
	v_exp_f32_e32 v24, v24
	v_mul_f32_e32 v20, 0x41800000, v20
	v_med3_f32 v20, v20, s93, v223
	v_add_f32_e32 v24, 1.0, v24
	v_rcp_f32_e32 v24, v24
	s_nop 0
	v_mul_f32_e32 v21, v24, v21
	v_mul_f32_e32 v24, v31, v0
	v_mul_f32_e32 v21, v24, v21
	v_mul_f32_e32 v24, 0xbfb8aa3b, v22
	v_exp_f32_e32 v24, v24
	v_mul_f32_e32 v21, 0x41800000, v21
	v_med3_f32 v21, v21, s93, v223
	v_add_f32_e32 v24, 1.0, v24
	v_rcp_f32_e32 v24, v24
	s_nop 0
	v_mul_f32_e32 v22, v24, v22
	v_mul_f32_e32 v24, v32, v0
	v_mul_f32_e32 v22, v24, v22
	v_mul_f32_e32 v24, 0xbfb8aa3b, v23
	v_exp_f32_e32 v24, v24
	v_mul_f32_e32 v22, 0x41800000, v22
	v_add_f32_e32 v24, 1.0, v24
	v_rcp_f32_e32 v24, v24
	s_nop 0
	v_mul_f32_e32 v23, v24, v23
	v_mul_f32_e32 v24, v33, v0
	v_mul_f32_e32 v23, v24, v23
	v_mov_b32_e32 v24, v1
	v_cvt_pk_fp8_f32 v24, v20, v21
	v_mul_f32_e32 v23, 0x41800000, v23
	v_med3_f32 v20, v22, s93, v223
	v_med3_f32 v21, v23, s93, v223
	v_cvt_pk_fp8_f32 v24, v20, v21 op_sel:[0,0,1]
	ds_write_b32 v212, v24 offset:24
	s_waitcnt vmcnt(7)
	v_lshlrev_b32_e32 v20, 16, v40
	v_mul_f32_e32 v24, 0xbfb8aa3b, v20
	v_exp_f32_e32 v24, v24
	v_and_b32_e32 v21, 0xffff0000, v40
	v_mul_f32_e32 v2, v2, v0
	v_lshlrev_b32_e32 v22, 16, v41
	v_add_f32_e32 v24, 1.0, v24
	v_rcp_f32_e32 v24, v24
	v_mul_f32_e32 v3, v3, v0
	v_and_b32_e32 v23, 0xffff0000, v41
	v_mul_f32_e32 v4, v4, v0
	v_mul_f32_e32 v20, v24, v20
	v_mul_f32_e32 v2, v2, v20
	v_mul_f32_e32 v20, 0xbfb8aa3b, v21
	v_exp_f32_e32 v20, v20
	v_mul_f32_e32 v5, v5, v0
	v_mul_f32_e32 v2, 0x41800000, v2
	v_med3_f32 v2, v2, s93, v223
	v_add_f32_e32 v20, 1.0, v20
	v_rcp_f32_e32 v20, v20
	s_nop 0
	v_mul_f32_e32 v20, v20, v21
	v_mul_f32_e32 v3, v3, v20
	v_mul_f32_e32 v20, 0xbfb8aa3b, v22
	v_exp_f32_e32 v20, v20
	v_mul_f32_e32 v3, 0x41800000, v3
	v_med3_f32 v3, v3, s93, v223
	v_add_f32_e32 v20, 1.0, v20
	v_rcp_f32_e32 v20, v20
	s_nop 0
	v_mul_f32_e32 v20, v20, v22
	v_mul_f32_e32 v4, v4, v20
	v_mul_f32_e32 v20, 0xbfb8aa3b, v23
	v_exp_f32_e32 v20, v20
	v_mul_f32_e32 v4, 0x41800000, v4
	v_add_f32_e32 v20, 1.0, v20
	v_rcp_f32_e32 v20, v20
	s_nop 0
	v_mul_f32_e32 v20, v20, v23
	v_mul_f32_e32 v5, v5, v20
	v_mov_b32_e32 v20, v1
	v_cvt_pk_fp8_f32 v20, v2, v3
	v_mul_f32_e32 v5, 0x41800000, v5
	v_med3_f32 v2, v4, s93, v223
	v_med3_f32 v3, v5, s93, v223
	v_cvt_pk_fp8_f32 v20, v2, v3 op_sel:[0,0,1]
	ds_write_b32 v212, v20 offset:32
	s_waitcnt vmcnt(7)
	v_lshlrev_b32_e32 v2, 16, v38
	v_mul_f32_e32 v20, 0xbfb8aa3b, v2
	v_exp_f32_e32 v20, v20
	v_and_b32_e32 v3, 0xffff0000, v38
	v_mul_f32_e32 v6, v6, v0
	v_lshlrev_b32_e32 v4, 16, v39
	v_add_f32_e32 v20, 1.0, v20
	v_rcp_f32_e32 v20, v20
	v_and_b32_e32 v5, 0xffff0000, v39
	v_mul_f32_e32 v2, v20, v2
	v_mul_f32_e32 v2, v6, v2
	v_mul_f32_e32 v6, 0xbfb8aa3b, v3
	v_exp_f32_e32 v6, v6
	v_mul_f32_e32 v2, 0x41800000, v2
	v_med3_f32 v2, v2, s93, v223
	v_add_f32_e32 v6, 1.0, v6
	v_rcp_f32_e32 v6, v6
	s_nop 0
	v_mul_f32_e32 v3, v6, v3
	v_mul_f32_e32 v6, v7, v0
	v_mul_f32_e32 v3, v6, v3
	v_mul_f32_e32 v6, 0xbfb8aa3b, v4
	v_exp_f32_e32 v6, v6
	v_mul_f32_e32 v3, 0x41800000, v3
	v_med3_f32 v3, v3, s93, v223
	v_add_f32_e32 v6, 1.0, v6
	v_rcp_f32_e32 v6, v6
	s_nop 0
	v_mul_f32_e32 v4, v6, v4
	v_mul_f32_e32 v6, v8, v0
	v_mul_f32_e32 v4, v6, v4
	v_mul_f32_e32 v6, 0xbfb8aa3b, v5
	v_exp_f32_e32 v6, v6
	v_mul_f32_e32 v4, 0x41800000, v4
	v_add_f32_e32 v6, 1.0, v6
	v_rcp_f32_e32 v6, v6
	s_nop 0
	v_mul_f32_e32 v5, v6, v5
	v_mul_f32_e32 v6, v9, v0
	v_mul_f32_e32 v5, v6, v5
	v_mov_b32_e32 v6, v1
	v_cvt_pk_fp8_f32 v6, v2, v3
	v_mul_f32_e32 v5, 0x41800000, v5
	v_med3_f32 v2, v4, s93, v223
	v_med3_f32 v3, v5, s93, v223
	v_cvt_pk_fp8_f32 v6, v2, v3 op_sel:[0,0,1]
	ds_write_b32 v212, v6 offset:40
	s_waitcnt vmcnt(7)
; DI float bf2f(unsigned b) { return __uint_as_float(b << 16); }
; template <int DQK, int W1, int DV, int VW, int MODE> ...
;     ...
; #pragma unroll
;   for (int cb = 0; cb < NCB; ++cb)
; #pragma unroll
;     for (int g = 0; g < 4; ++g) {
;       const int dv = 32 * cb + 8 * g + 4 * hi;
;       const u32x2 gg = ggv[cb * 4 + g];
;       float gv[4] = {bf2f(gg[0] & 0xffffu), bf2f(gg[0] >> 16), bf2f(gg[1] & 0xffffu), bf2f(gg[1] >> 16)};
;       float ov[4];
; #pragma unroll
;       for (int j = 0; j < 4; ++j) {
;         const float sg = gv[j] * __builtin_amdgcn_rcpf(1.f + __builtin_amdgcn_exp2f(-LOG2E * gv[j]));
;         ov[j] = o[cb][4 * g + j] * inv * sg;
;       }
;       *(unsigned*)((unsigned char*)yrow + dv) = pk4_fp8(ov[0] * Y_SCALE, ov[1] * Y_SCALE, ov[2] * Y_SCALE, ov[3] * Y_SCALE);
;       __builtin_amdgcn_sched_barrier(0);
;     }
	v_lshlrev_b32_e32 v2, 16, v36
	v_mul_f32_e32 v6, 0xbfb8aa3b, v2
	v_exp_f32_e32 v6, v6
	v_and_b32_e32 v3, 0xffff0000, v36
	v_lshlrev_b32_e32 v4, 16, v37
	v_and_b32_e32 v5, 0xffff0000, v37
	v_add_f32_e32 v6, 1.0, v6
	v_rcp_f32_e32 v6, v6
	s_nop 0
	v_mul_f32_e32 v2, v6, v2
	v_mul_f32_e32 v6, v10, v0
	v_mul_f32_e32 v2, v6, v2
	v_mul_f32_e32 v6, 0xbfb8aa3b, v3
	v_exp_f32_e32 v6, v6
	v_mul_f32_e32 v2, 0x41800000, v2
	v_med3_f32 v2, v2, s93, v223
	v_add_f32_e32 v6, 1.0, v6
	v_rcp_f32_e32 v6, v6
	s_nop 0
	v_mul_f32_e32 v3, v6, v3
	v_mul_f32_e32 v6, v11, v0
	v_mul_f32_e32 v3, v6, v3
	v_mul_f32_e32 v6, 0xbfb8aa3b, v4
	v_exp_f32_e32 v6, v6
	v_mul_f32_e32 v3, 0x41800000, v3
	v_med3_f32 v3, v3, s93, v223
	v_add_f32_e32 v6, 1.0, v6
	v_rcp_f32_e32 v6, v6
	s_nop 0
	v_mul_f32_e32 v4, v6, v4
	v_mul_f32_e32 v6, v12, v0
	v_mul_f32_e32 v4, v6, v4
	v_mul_f32_e32 v6, 0xbfb8aa3b, v5
	v_exp_f32_e32 v6, v6
	v_mul_f32_e32 v4, 0x41800000, v4
	v_add_f32_e32 v6, 1.0, v6
	v_rcp_f32_e32 v6, v6
	s_nop 0
	v_mul_f32_e32 v5, v6, v5
	v_mul_f32_e32 v6, v13, v0
	v_mul_f32_e32 v5, v6, v5
	v_mov_b32_e32 v6, v1
	v_cvt_pk_fp8_f32 v6, v2, v3
	v_mul_f32_e32 v5, 0x41800000, v5
	v_med3_f32 v2, v4, s93, v223
	v_med3_f32 v3, v5, s93, v223
	v_cvt_pk_fp8_f32 v6, v2, v3 op_sel:[0,0,1]
	ds_write_b32 v212, v6 offset:48
	s_waitcnt vmcnt(7)
	v_lshlrev_b32_e32 v2, 16, v34
	v_mul_f32_e32 v6, 0xbfb8aa3b, v2
	v_exp_f32_e32 v6, v6
	v_and_b32_e32 v3, 0xffff0000, v34
	v_lshlrev_b32_e32 v4, 16, v35
	v_and_b32_e32 v5, 0xffff0000, v35
	v_add_f32_e32 v6, 1.0, v6
	v_rcp_f32_e32 v6, v6
	s_nop 0
	v_mul_f32_e32 v2, v6, v2
	v_mul_f32_e32 v6, v14, v0
	v_mul_f32_e32 v2, v6, v2
	v_mul_f32_e32 v6, 0xbfb8aa3b, v3
	v_exp_f32_e32 v6, v6
	v_mul_f32_e32 v2, 0x41800000, v2
	v_med3_f32 v2, v2, s93, v223
	v_add_f32_e32 v6, 1.0, v6
	v_rcp_f32_e32 v6, v6
	s_nop 0
	v_mul_f32_e32 v3, v6, v3
	v_mul_f32_e32 v6, v15, v0
	v_mul_f32_e32 v3, v6, v3
	v_mul_f32_e32 v6, 0xbfb8aa3b, v4
	v_exp_f32_e32 v6, v6
	v_mul_f32_e32 v3, 0x41800000, v3
	v_med3_f32 v3, v3, s93, v223
	v_add_f32_e32 v6, 1.0, v6
	v_rcp_f32_e32 v6, v6
	s_nop 0
	v_mul_f32_e32 v4, v6, v4
	v_mul_f32_e32 v6, v16, v0
	v_mul_f32_e32 v4, v6, v4
	v_mul_f32_e32 v6, 0xbfb8aa3b, v5
	v_exp_f32_e32 v6, v6
	v_mul_f32_e32 v0, v17, v0
	v_mul_f32_e32 v4, 0x41800000, v4
	v_add_f32_e32 v6, 1.0, v6
	v_rcp_f32_e32 v6, v6
	s_nop 0
	v_mul_f32_e32 v5, v6, v5
	v_mul_f32_e32 v0, v0, v5
	v_mov_b32_e32 v5, v1
	v_cvt_pk_fp8_f32 v5, v2, v3
	v_mul_f32_e32 v0, 0x41800000, v0
	v_med3_f32 v2, v4, s93, v223
	v_med3_f32 v0, v0, s93, v223
	v_cvt_pk_fp8_f32 v5, v2, v0 op_sel:[0,0,1]
	ds_write_b32 v212, v5 offset:56
	v_readfirstlane_b32 s0, v18
	v_readfirstlane_b32 s1, v19
	s_waitcnt lgkmcnt(0)
	ds_read_b64 v[2:3], v211
	ds_read_b64 v[4:5], v211 offset:8
	ds_read_b64 v[6:7], v211 offset:1152
	ds_read_b64 v[8:9], v211 offset:1160
	v_add_u32_e32 v213, 0xc000, v210
	s_waitcnt lgkmcnt(0)
	global_store_dwordx4 v210, v[2:5], s[0:1]
	global_store_dwordx4 v213, v[6:9], s[0:1]
	s_movk_i32 s20, 0x600
	s_mov_b32 s86, 0x800000
	s_movk_i32 s87, 0x3fff
	v_readlane_b32 s3, v254, 29
